# accumulator zero-init of all 7 GEMM instantiations: 64 v_mov_b64 instead of 128 v_mov_b32 copies
# speedup vs baseline: 1.0185x; 1.0049x over previous
.LBB0_453:
	s_add_u32 s2, s2, 0x40080
	s_addc_u32 s3, s3, 0
	s_add_u32 s6, s0, 0x100
	s_addc_u32 s7, s1, 0
	s_mov_b32 s8, -2
	s_mov_b64 s[58:59], 0x80
	v_mov_b64_e32 v[0:1], 0
	v_mov_b64_e32 v[2:3], 0
	v_mov_b64_e32 v[4:5], 0
	v_mov_b64_e32 v[6:7], 0
	v_mov_b64_e32 v[8:9], 0
	v_mov_b64_e32 v[10:11], 0
	v_mov_b64_e32 v[12:13], 0
	v_mov_b64_e32 v[14:15], 0
	v_mov_b64_e32 v[16:17], 0
	v_mov_b64_e32 v[18:19], 0
	v_mov_b64_e32 v[20:21], 0
	v_mov_b64_e32 v[22:23], 0
	v_mov_b64_e32 v[24:25], 0
	v_mov_b64_e32 v[26:27], 0
	v_mov_b64_e32 v[28:29], 0
	v_mov_b64_e32 v[30:31], 0
	v_mov_b64_e32 v[32:33], 0
	v_mov_b64_e32 v[34:35], 0
	v_mov_b64_e32 v[36:37], 0
	v_mov_b64_e32 v[38:39], 0
	v_mov_b64_e32 v[40:41], 0
	v_mov_b64_e32 v[42:43], 0
	v_mov_b64_e32 v[44:45], 0
	v_mov_b64_e32 v[46:47], 0
	v_mov_b64_e32 v[48:49], 0
	v_mov_b64_e32 v[50:51], 0
	v_mov_b64_e32 v[52:53], 0
	v_mov_b64_e32 v[54:55], 0
	v_mov_b64_e32 v[56:57], 0
	v_mov_b64_e32 v[58:59], 0
	v_mov_b64_e32 v[60:61], 0
	v_mov_b64_e32 v[62:63], 0
	v_mov_b64_e32 v[64:65], 0
	v_mov_b64_e32 v[66:67], 0
	v_mov_b64_e32 v[68:69], 0
	v_mov_b64_e32 v[70:71], 0
	v_mov_b64_e32 v[72:73], 0
	v_mov_b64_e32 v[74:75], 0
	v_mov_b64_e32 v[76:77], 0
	v_mov_b64_e32 v[78:79], 0
	v_mov_b64_e32 v[80:81], 0
	v_mov_b64_e32 v[82:83], 0
	v_mov_b64_e32 v[84:85], 0
	v_mov_b64_e32 v[86:87], 0
	v_mov_b64_e32 v[88:89], 0
	v_mov_b64_e32 v[90:91], 0
	v_mov_b64_e32 v[92:93], 0
	v_mov_b64_e32 v[94:95], 0
	v_mov_b64_e32 v[96:97], 0
	v_mov_b64_e32 v[98:99], 0
	v_mov_b64_e32 v[100:101], 0
	v_mov_b64_e32 v[102:103], 0
	v_mov_b64_e32 v[104:105], 0
	v_mov_b64_e32 v[106:107], 0
	v_mov_b64_e32 v[108:109], 0
	v_mov_b64_e32 v[110:111], 0
	v_mov_b64_e32 v[116:117], 0
	v_mov_b64_e32 v[118:119], 0
	v_mov_b64_e32 v[120:121], 0
	v_mov_b64_e32 v[122:123], 0
	v_mov_b64_e32 v[124:125], 0
	v_mov_b64_e32 v[126:127], 0
	v_mov_b64_e32 v[128:129], 0
	v_mov_b64_e32 v[130:131], 0

.LBB0_526:
	s_add_u32 s36, s36, 0x40080
	s_addc_u32 s37, s37, 0
	s_add_u32 s9, s4, 0x100
	s_addc_u32 s33, s5, 0
	s_mov_b32 s46, -2
	s_mov_b64 s[58:59], 0x80
	v_mov_b64_e32 v[0:1], 0
	v_mov_b64_e32 v[2:3], 0
	v_mov_b64_e32 v[4:5], 0
	v_mov_b64_e32 v[6:7], 0
	v_mov_b64_e32 v[8:9], 0
	v_mov_b64_e32 v[10:11], 0
	v_mov_b64_e32 v[12:13], 0
	v_mov_b64_e32 v[14:15], 0
	v_mov_b64_e32 v[16:17], 0
	v_mov_b64_e32 v[18:19], 0
	v_mov_b64_e32 v[20:21], 0
	v_mov_b64_e32 v[22:23], 0
	v_mov_b64_e32 v[24:25], 0
	v_mov_b64_e32 v[26:27], 0
	v_mov_b64_e32 v[28:29], 0
	v_mov_b64_e32 v[30:31], 0
	v_mov_b64_e32 v[32:33], 0
	v_mov_b64_e32 v[34:35], 0
	v_mov_b64_e32 v[36:37], 0
	v_mov_b64_e32 v[38:39], 0
	v_mov_b64_e32 v[40:41], 0
	v_mov_b64_e32 v[42:43], 0
	v_mov_b64_e32 v[44:45], 0
	v_mov_b64_e32 v[46:47], 0
	v_mov_b64_e32 v[48:49], 0
	v_mov_b64_e32 v[50:51], 0
	v_mov_b64_e32 v[52:53], 0
	v_mov_b64_e32 v[54:55], 0
	v_mov_b64_e32 v[56:57], 0
	v_mov_b64_e32 v[58:59], 0
	v_mov_b64_e32 v[60:61], 0
	v_mov_b64_e32 v[62:63], 0
	v_mov_b64_e32 v[64:65], 0
	v_mov_b64_e32 v[66:67], 0
	v_mov_b64_e32 v[68:69], 0
	v_mov_b64_e32 v[70:71], 0
	v_mov_b64_e32 v[72:73], 0
	v_mov_b64_e32 v[74:75], 0
	v_mov_b64_e32 v[76:77], 0
	v_mov_b64_e32 v[78:79], 0
	v_mov_b64_e32 v[80:81], 0
	v_mov_b64_e32 v[82:83], 0
	v_mov_b64_e32 v[84:85], 0
	v_mov_b64_e32 v[86:87], 0
	v_mov_b64_e32 v[88:89], 0
	v_mov_b64_e32 v[90:91], 0
	v_mov_b64_e32 v[92:93], 0
	v_mov_b64_e32 v[94:95], 0
	v_mov_b64_e32 v[96:97], 0
	v_mov_b64_e32 v[98:99], 0
	v_mov_b64_e32 v[100:101], 0
	v_mov_b64_e32 v[102:103], 0
	v_mov_b64_e32 v[104:105], 0
	v_mov_b64_e32 v[106:107], 0
	v_mov_b64_e32 v[108:109], 0
	v_mov_b64_e32 v[110:111], 0
	v_mov_b64_e32 v[112:113], 0
	v_mov_b64_e32 v[114:115], 0
	v_mov_b64_e32 v[116:117], 0
	v_mov_b64_e32 v[118:119], 0
	v_mov_b64_e32 v[120:121], 0
	v_mov_b64_e32 v[122:123], 0
	v_mov_b64_e32 v[124:125], 0
	v_mov_b64_e32 v[126:127], 0

.LBB0_581:
	s_add_u32 s50, s6, 0x80
	s_addc_u32 s51, s7, 0
	s_add_u32 s41, s48, 0x100
	v_lshl_add_u64 v[128:129], s[50:51], 0, v[152:153]
	v_lshl_add_u64 v[130:131], s[50:51], 0, v[154:155]
	s_addc_u32 s43, s49, 0
	s_mov_b32 vcc_lo, -2
	s_mov_b64 s[48:49], 0
	s_mov_b64 s[64:65], 0x80
	v_mov_b64_e32 v[0:1], 0
	v_mov_b64_e32 v[2:3], 0
	v_mov_b64_e32 v[4:5], 0
	v_mov_b64_e32 v[6:7], 0
	v_mov_b64_e32 v[8:9], 0
	v_mov_b64_e32 v[10:11], 0
	v_mov_b64_e32 v[12:13], 0
	v_mov_b64_e32 v[14:15], 0
	v_mov_b64_e32 v[16:17], 0
	v_mov_b64_e32 v[18:19], 0
	v_mov_b64_e32 v[20:21], 0
	v_mov_b64_e32 v[22:23], 0
	v_mov_b64_e32 v[24:25], 0
	v_mov_b64_e32 v[26:27], 0
	v_mov_b64_e32 v[28:29], 0
	v_mov_b64_e32 v[30:31], 0
	v_mov_b64_e32 v[32:33], 0
	v_mov_b64_e32 v[34:35], 0
	v_mov_b64_e32 v[36:37], 0
	v_mov_b64_e32 v[38:39], 0
	v_mov_b64_e32 v[40:41], 0
	v_mov_b64_e32 v[42:43], 0
	v_mov_b64_e32 v[44:45], 0
	v_mov_b64_e32 v[46:47], 0
	v_mov_b64_e32 v[48:49], 0
	v_mov_b64_e32 v[50:51], 0
	v_mov_b64_e32 v[52:53], 0
	v_mov_b64_e32 v[54:55], 0
	v_mov_b64_e32 v[56:57], 0
	v_mov_b64_e32 v[58:59], 0
	v_mov_b64_e32 v[60:61], 0
	v_mov_b64_e32 v[62:63], 0
	v_mov_b64_e32 v[64:65], 0
	v_mov_b64_e32 v[66:67], 0
	v_mov_b64_e32 v[68:69], 0
	v_mov_b64_e32 v[70:71], 0
	v_mov_b64_e32 v[72:73], 0
	v_mov_b64_e32 v[74:75], 0
	v_mov_b64_e32 v[76:77], 0
	v_mov_b64_e32 v[78:79], 0
	v_mov_b64_e32 v[80:81], 0
	v_mov_b64_e32 v[82:83], 0
	v_mov_b64_e32 v[84:85], 0
	v_mov_b64_e32 v[86:87], 0
	v_mov_b64_e32 v[88:89], 0
	v_mov_b64_e32 v[90:91], 0
	v_mov_b64_e32 v[92:93], 0
	v_mov_b64_e32 v[94:95], 0
	v_mov_b64_e32 v[96:97], 0
	v_mov_b64_e32 v[98:99], 0
	v_mov_b64_e32 v[100:101], 0
	v_mov_b64_e32 v[102:103], 0
	v_mov_b64_e32 v[104:105], 0
	v_mov_b64_e32 v[106:107], 0
	v_mov_b64_e32 v[108:109], 0
	v_mov_b64_e32 v[110:111], 0
	v_mov_b64_e32 v[112:113], 0
	v_mov_b64_e32 v[114:115], 0
	v_mov_b64_e32 v[116:117], 0
	v_mov_b64_e32 v[118:119], 0
	v_mov_b64_e32 v[120:121], 0
	v_mov_b64_e32 v[122:123], 0
	v_mov_b64_e32 v[124:125], 0
	v_mov_b64_e32 v[126:127], 0

.LBB0_634:
	s_add_u32 s2, s2, 0x40080
	s_addc_u32 s3, s3, 0
	s_add_u32 s1, s6, 0x100
	s_addc_u32 s8, s7, 0
	s_mov_b32 s9, -2
	s_mov_b64 s[58:59], 0x80
	v_mov_b64_e32 v[0:1], 0
	v_mov_b64_e32 v[2:3], 0
	v_mov_b64_e32 v[4:5], 0
	v_mov_b64_e32 v[6:7], 0
	v_mov_b64_e32 v[8:9], 0
	v_mov_b64_e32 v[10:11], 0
	v_mov_b64_e32 v[12:13], 0
	v_mov_b64_e32 v[14:15], 0
	v_mov_b64_e32 v[16:17], 0
	v_mov_b64_e32 v[18:19], 0
	v_mov_b64_e32 v[20:21], 0
	v_mov_b64_e32 v[22:23], 0
	v_mov_b64_e32 v[24:25], 0
	v_mov_b64_e32 v[26:27], 0
	v_mov_b64_e32 v[28:29], 0
	v_mov_b64_e32 v[30:31], 0
	v_mov_b64_e32 v[40:41], 0
	v_mov_b64_e32 v[42:43], 0
	v_mov_b64_e32 v[44:45], 0
	v_mov_b64_e32 v[46:47], 0
	v_mov_b64_e32 v[48:49], 0
	v_mov_b64_e32 v[50:51], 0
	v_mov_b64_e32 v[52:53], 0
	v_mov_b64_e32 v[54:55], 0
	v_mov_b64_e32 v[56:57], 0
	v_mov_b64_e32 v[58:59], 0
	v_mov_b64_e32 v[60:61], 0
	v_mov_b64_e32 v[62:63], 0
	v_mov_b64_e32 v[64:65], 0
	v_mov_b64_e32 v[66:67], 0
	v_mov_b64_e32 v[68:69], 0
	v_mov_b64_e32 v[70:71], 0
	v_mov_b64_e32 v[80:81], 0
	v_mov_b64_e32 v[82:83], 0
	v_mov_b64_e32 v[84:85], 0
	v_mov_b64_e32 v[86:87], 0
	v_mov_b64_e32 v[88:89], 0
	v_mov_b64_e32 v[90:91], 0
	v_mov_b64_e32 v[92:93], 0
	v_mov_b64_e32 v[94:95], 0
	v_mov_b64_e32 v[96:97], 0
	v_mov_b64_e32 v[98:99], 0
	v_mov_b64_e32 v[100:101], 0
	v_mov_b64_e32 v[102:103], 0
	v_mov_b64_e32 v[104:105], 0
	v_mov_b64_e32 v[106:107], 0
	v_mov_b64_e32 v[108:109], 0
	v_mov_b64_e32 v[110:111], 0
	v_mov_b64_e32 v[120:121], 0
	v_mov_b64_e32 v[122:123], 0
	v_mov_b64_e32 v[124:125], 0
	v_mov_b64_e32 v[126:127], 0
	v_mov_b64_e32 v[128:129], 0
	v_mov_b64_e32 v[130:131], 0
	v_mov_b64_e32 v[132:133], 0
	v_mov_b64_e32 v[134:135], 0
	v_mov_b64_e32 v[136:137], 0
	v_mov_b64_e32 v[138:139], 0
	v_mov_b64_e32 v[140:141], 0
	v_mov_b64_e32 v[142:143], 0
	v_mov_b64_e32 v[144:145], 0
	v_mov_b64_e32 v[146:147], 0
	v_mov_b64_e32 v[148:149], 0
	v_mov_b64_e32 v[150:151], 0

.LBB0_1009:
	s_add_u32 s36, s36, 0x80
	s_addc_u32 s37, s37, 0
	s_add_u32 s8, s6, 0x100
	s_addc_u32 s9, s7, 0
	s_mov_b32 s6, 0
	s_mov_b64 s[58:59], s[10:11]
	s_mov_b64 s[64:65], 0x80
	v_mov_b64_e32 v[0:1], 0
	v_mov_b64_e32 v[2:3], 0
	v_mov_b64_e32 v[4:5], 0
	v_mov_b64_e32 v[6:7], 0
	v_mov_b64_e32 v[8:9], 0
	v_mov_b64_e32 v[10:11], 0
	v_mov_b64_e32 v[12:13], 0
	v_mov_b64_e32 v[14:15], 0
	v_mov_b64_e32 v[16:17], 0
	v_mov_b64_e32 v[18:19], 0
	v_mov_b64_e32 v[20:21], 0
	v_mov_b64_e32 v[22:23], 0
	v_mov_b64_e32 v[24:25], 0
	v_mov_b64_e32 v[26:27], 0
	v_mov_b64_e32 v[28:29], 0
	v_mov_b64_e32 v[30:31], 0
	v_mov_b64_e32 v[32:33], 0
	v_mov_b64_e32 v[34:35], 0
	v_mov_b64_e32 v[36:37], 0
	v_mov_b64_e32 v[38:39], 0
	v_mov_b64_e32 v[40:41], 0
	v_mov_b64_e32 v[42:43], 0
	v_mov_b64_e32 v[44:45], 0
	v_mov_b64_e32 v[46:47], 0
	v_mov_b64_e32 v[48:49], 0
	v_mov_b64_e32 v[50:51], 0
	v_mov_b64_e32 v[52:53], 0
	v_mov_b64_e32 v[54:55], 0
	v_mov_b64_e32 v[56:57], 0
	v_mov_b64_e32 v[58:59], 0
	v_mov_b64_e32 v[60:61], 0
	v_mov_b64_e32 v[62:63], 0
	v_mov_b64_e32 v[64:65], 0
	v_mov_b64_e32 v[66:67], 0
	v_mov_b64_e32 v[68:69], 0
	v_mov_b64_e32 v[70:71], 0
	v_mov_b64_e32 v[72:73], 0
	v_mov_b64_e32 v[74:75], 0
	v_mov_b64_e32 v[76:77], 0
	v_mov_b64_e32 v[78:79], 0
	v_mov_b64_e32 v[80:81], 0
	v_mov_b64_e32 v[82:83], 0
	v_mov_b64_e32 v[84:85], 0
	v_mov_b64_e32 v[86:87], 0
	v_mov_b64_e32 v[88:89], 0
	v_mov_b64_e32 v[90:91], 0
	v_mov_b64_e32 v[92:93], 0
	v_mov_b64_e32 v[94:95], 0
	v_mov_b64_e32 v[96:97], 0
	v_mov_b64_e32 v[98:99], 0
	v_mov_b64_e32 v[100:101], 0
	v_mov_b64_e32 v[102:103], 0
	v_mov_b64_e32 v[104:105], 0
	v_mov_b64_e32 v[106:107], 0
	v_mov_b64_e32 v[108:109], 0
	v_mov_b64_e32 v[110:111], 0
	v_mov_b64_e32 v[112:113], 0
	v_mov_b64_e32 v[114:115], 0
	v_mov_b64_e32 v[116:117], 0
	v_mov_b64_e32 v[118:119], 0
	v_mov_b64_e32 v[120:121], 0
	v_mov_b64_e32 v[122:123], 0
	v_mov_b64_e32 v[124:125], 0
	v_mov_b64_e32 v[126:127], 0

.LBB0_1083:
	s_add_u32 s0, s0, 0x40080
	s_addc_u32 s1, s1, 0
	s_add_u32 s9, s2, 0x100
	s_addc_u32 s36, s3, 0
	s_mov_b32 s37, -2
	s_mov_b64 s[64:65], 0x80
	v_mov_b64_e32 v[0:1], 0
	v_mov_b64_e32 v[2:3], 0
	v_mov_b64_e32 v[4:5], 0
	v_mov_b64_e32 v[6:7], 0
	v_mov_b64_e32 v[8:9], 0
	v_mov_b64_e32 v[10:11], 0
	v_mov_b64_e32 v[12:13], 0
	v_mov_b64_e32 v[14:15], 0
	v_mov_b64_e32 v[16:17], 0
	v_mov_b64_e32 v[18:19], 0
	v_mov_b64_e32 v[20:21], 0
	v_mov_b64_e32 v[22:23], 0
	v_mov_b64_e32 v[24:25], 0
	v_mov_b64_e32 v[26:27], 0
	v_mov_b64_e32 v[28:29], 0
	v_mov_b64_e32 v[30:31], 0
	v_mov_b64_e32 v[32:33], 0
	v_mov_b64_e32 v[34:35], 0
	v_mov_b64_e32 v[36:37], 0
	v_mov_b64_e32 v[38:39], 0
	v_mov_b64_e32 v[40:41], 0
	v_mov_b64_e32 v[42:43], 0
	v_mov_b64_e32 v[44:45], 0
	v_mov_b64_e32 v[46:47], 0
	v_mov_b64_e32 v[48:49], 0
	v_mov_b64_e32 v[50:51], 0
	v_mov_b64_e32 v[52:53], 0
	v_mov_b64_e32 v[54:55], 0
	v_mov_b64_e32 v[56:57], 0
	v_mov_b64_e32 v[58:59], 0
	v_mov_b64_e32 v[60:61], 0
	v_mov_b64_e32 v[62:63], 0
	v_mov_b64_e32 v[64:65], 0
	v_mov_b64_e32 v[66:67], 0
	v_mov_b64_e32 v[68:69], 0
	v_mov_b64_e32 v[70:71], 0
	v_mov_b64_e32 v[72:73], 0
	v_mov_b64_e32 v[74:75], 0
	v_mov_b64_e32 v[76:77], 0
	v_mov_b64_e32 v[78:79], 0
	v_mov_b64_e32 v[80:81], 0
	v_mov_b64_e32 v[82:83], 0
	v_mov_b64_e32 v[84:85], 0
	v_mov_b64_e32 v[86:87], 0
	v_mov_b64_e32 v[88:89], 0
	v_mov_b64_e32 v[90:91], 0
	v_mov_b64_e32 v[92:93], 0
	v_mov_b64_e32 v[94:95], 0
	v_mov_b64_e32 v[96:97], 0
	v_mov_b64_e32 v[98:99], 0
	v_mov_b64_e32 v[100:101], 0
	v_mov_b64_e32 v[102:103], 0
	v_mov_b64_e32 v[104:105], 0
	v_mov_b64_e32 v[106:107], 0
	v_mov_b64_e32 v[108:109], 0
	v_mov_b64_e32 v[110:111], 0
	v_mov_b64_e32 v[112:113], 0
	v_mov_b64_e32 v[114:115], 0
	v_mov_b64_e32 v[116:117], 0
	v_mov_b64_e32 v[118:119], 0
	v_mov_b64_e32 v[120:121], 0
	v_mov_b64_e32 v[122:123], 0
	v_mov_b64_e32 v[124:125], 0
	v_mov_b64_e32 v[126:127], 0

.LBB0_1136:
	s_add_u32 s44, s44, 0x80
	s_addc_u32 s45, s45, 0
	s_add_u32 s25, s42, 0x100
	s_addc_u32 s46, s43, 0
	s_mov_b32 s42, 0
	s_mov_b64 s[10:11], 0x80
	v_mov_b64_e32 v[0:1], 0
	v_mov_b64_e32 v[2:3], 0
	v_mov_b64_e32 v[4:5], 0
	v_mov_b64_e32 v[6:7], 0
	v_mov_b64_e32 v[8:9], 0
	v_mov_b64_e32 v[10:11], 0
	v_mov_b64_e32 v[12:13], 0
	v_mov_b64_e32 v[14:15], 0
	v_mov_b64_e32 v[16:17], 0
	v_mov_b64_e32 v[18:19], 0
	v_mov_b64_e32 v[20:21], 0
	v_mov_b64_e32 v[22:23], 0
	v_mov_b64_e32 v[24:25], 0
	v_mov_b64_e32 v[26:27], 0
	v_mov_b64_e32 v[28:29], 0
	v_mov_b64_e32 v[30:31], 0
	v_mov_b64_e32 v[32:33], 0
	v_mov_b64_e32 v[34:35], 0
	v_mov_b64_e32 v[36:37], 0
	v_mov_b64_e32 v[38:39], 0
	v_mov_b64_e32 v[40:41], 0
	v_mov_b64_e32 v[42:43], 0
	v_mov_b64_e32 v[44:45], 0
	v_mov_b64_e32 v[46:47], 0
	v_mov_b64_e32 v[48:49], 0
	v_mov_b64_e32 v[50:51], 0
	v_mov_b64_e32 v[52:53], 0
	v_mov_b64_e32 v[54:55], 0
	v_mov_b64_e32 v[56:57], 0
	v_mov_b64_e32 v[58:59], 0
	v_mov_b64_e32 v[60:61], 0
	v_mov_b64_e32 v[62:63], 0
	v_mov_b64_e32 v[64:65], 0
	v_mov_b64_e32 v[66:67], 0
	v_mov_b64_e32 v[68:69], 0
	v_mov_b64_e32 v[70:71], 0
	v_mov_b64_e32 v[72:73], 0
	v_mov_b64_e32 v[74:75], 0
	v_mov_b64_e32 v[76:77], 0
	v_mov_b64_e32 v[78:79], 0
	v_mov_b64_e32 v[80:81], 0
	v_mov_b64_e32 v[82:83], 0
	v_mov_b64_e32 v[84:85], 0
	v_mov_b64_e32 v[86:87], 0
	v_mov_b64_e32 v[88:89], 0
	v_mov_b64_e32 v[90:91], 0
	v_mov_b64_e32 v[92:93], 0
	v_mov_b64_e32 v[94:95], 0
	v_mov_b64_e32 v[96:97], 0
	v_mov_b64_e32 v[98:99], 0
	v_mov_b64_e32 v[100:101], 0
	v_mov_b64_e32 v[102:103], 0
	v_mov_b64_e32 v[104:105], 0
	v_mov_b64_e32 v[106:107], 0
	v_mov_b64_e32 v[108:109], 0
	v_mov_b64_e32 v[110:111], 0
	v_mov_b64_e32 v[112:113], 0
	v_mov_b64_e32 v[114:115], 0
	v_mov_b64_e32 v[116:117], 0
	v_mov_b64_e32 v[118:119], 0
	v_mov_b64_e32 v[120:121], 0
	v_mov_b64_e32 v[122:123], 0
	v_mov_b64_e32 v[124:125], 0
	v_mov_b64_e32 v[126:127], 0
